# speedup vs baseline: 1.0082x; 1.0017x over previous
.LBB0_601:
	s_or_b64 exec, exec, s[0:1]
	s_lshl_b32 s2, s70, 9
	v_add_u32_e32 v0, s2, v218
	v_and_b32_e32 v0, 0xffff, v0
	v_lshlrev_b32_e32 v0, 7, v0
	s_add_u32 s4, s60, 0x1500000
	s_addc_u32 s5, s61, 0
	global_load_dword v250, v0, s[4:5]
	v_mov_b32_e32 v220, v218
	s_cmpk_lt_i32 s70, 0x200
	s_waitcnt lgkmcnt(0)
	s_barrier
	s_cselect_b64 s[10:11], -1, 0
	s_cmpk_gt_i32 s70, 0x1ff
	v_readfirstlane_b32 s12, v220
	s_cbranch_scc1 .LBB0_604
	s_and_b32 s99, s70, 1
	s_lshl_b32 s99, s99, 8
	s_add_i32 s99, s99, s70
	s_ashr_i32 s0, s99, 31
	s_lshr_b32 s0, s0, 29
	s_add_i32 s2, s99, s0
	s_and_b32 s0, s2, -8
	s_sub_i32 s3, s99, s0
	s_cmp_gt_i32 s3, -1
	s_cbranch_scc0 .LBB0_605
	s_lshl_b32 s4, s3, 6
	s_cbranch_execz .LBB0_606
	s_branch .LBB0_607

.LBB0_988:
	s_or_b64 exec, exec, s[0:1]
	s_lshl_b32 s2, s70, 9
	v_add_u32_e32 v0, s2, v218
	v_lshlrev_b32_e32 v0, 7, v0
	s_add_u32 s4, s60, 0x3d00000
	s_addc_u32 s5, s61, 0
	global_load_dword v250, v0, s[4:5]
	s_add_u32 s4, s4, 0x1000000
	s_addc_u32 s5, s5, 0
	global_load_dword v251, v0, s[4:5]
	s_add_u32 s10, s60, 0x10000000
	s_addc_u32 s11, s61, 0
	v_mov_b32_e32 v144, v218
	s_waitcnt lgkmcnt(0)
	s_barrier
	s_cmpk_gt_i32 s70, 0x7ff
	v_readfirstlane_b32 s15, v144
	s_cbranch_scc1 .LBB0_1012
	s_and_b32 s99, s70, 7
	s_lshl_b32 s99, s99, 8
	s_add_i32 s99, s99, s70
	s_ashr_i32 s0, s99, 31
	s_lshr_b32 s0, s0, 29
	s_add_i32 s3, s99, s0
	s_and_b32 s0, s3, -8
	s_sub_i32 s2, s99, s0
	s_cmp_gt_i32 s2, -1
	s_cbranch_scc0 .LBB0_991
	s_lshl_b32 s4, s2, 8
	s_cbranch_execz .LBB0_992
	s_branch .LBB0_993

.LBB0_1064:
	s_or_b64 exec, exec, s[0:1]
	s_lshl_b32 s2, s70, 9
	v_add_u32_e32 v0, s2, v218
	v_lshlrev_b32_e32 v0, 7, v0
	s_add_u32 s4, s60, 0x5d00000
	s_addc_u32 s5, s61, 0
	global_load_dword v250, v0, s[4:5]
	s_add_u32 s4, s4, 0x1000000
	s_addc_u32 s5, s5, 0
	global_load_dword v251, v0, s[4:5]
	v_mov_b32_e32 v154, v218
	s_waitcnt lgkmcnt(0)
	s_barrier
	s_and_b64 vcc, exec, s[8:9]
	v_readfirstlane_b32 s7, v154
	s_cbranch_vccnz .LBB0_1088
	s_and_b32 s99, s70, 1
	s_lshl_b32 s99, s99, 8
	s_add_i32 s99, s99, s70
	s_ashr_i32 s0, s99, 31
	s_lshr_b32 s0, s0, 29
	s_add_i32 s4, s99, s0
	s_and_b32 s0, s4, -8
	s_sub_i32 s2, s99, s0
	s_cmp_gt_i32 s2, -1
	s_cbranch_scc0 .LBB0_1067
	s_lshl_b32 s3, s2, 6
	s_ashr_i32 s0, s4, 3
	s_cbranch_execz .LBB0_1068
	s_branch .LBB0_1069
